# k0 weight conversion rewritten by hand: per-wave 64x64 tiles, 64 loads in flight, LDS-slab transpose, full-line bf16 stores
# speedup vs baseline: 1.0134x; 1.0092x over previous
; #define LAS __attribute__((address_space(3)))
; #define LBAR() do { asm volatile("s_waitcnt lgkmcnt(0)" ::: "memory"); __builtin_amdgcn_s_barrier(); asm volatile("" ::: "memory"); } while (0)
; __device__ __forceinline__ void convert_weights(const int TID, const int BID, const Params& p, int l, LAS float* tile) {
;     const int G = gridDim.x, b = BID;
;     bf16_t* btin = (bf16_t*)(p.ws + WS_BTIN); bf16_t* btout = (bf16_t*)(p.ws + WS_BTOUT); bf16_t* bto = (bf16_t*)(p.ws + WS_BTO); bf16_t* btglu = (bf16_t*)(p.ws + WS_BTGLU); bf16_t* btlru = (bf16_t*)(p.ws + WS_BTLRU);
;     { const float* src = p.in[4] + (size_t)l * D * NIN; const int tx = TID & 63, ty = TID >> 6; float v[8];
;       { const int t = b < 32 * 169 ? b : 0; const int kt = t / 169, ntl = t - kt * 169; const int ncl = (ntl * 64 + tx < NIN) ? ntl * 64 + tx : NIN - 1;
; #pragma unroll
;         for (int i = 0; i < 8; ++i) v[i] = src[(size_t)(kt * 64 + ty + 8 * i) * NIN + ncl]; }
;       for (int t = b; t < 32 * 169; t += G) { const int kt = t / 169, ntl = t - kt * 169, k0 = kt * 64, n0 = ntl * 64;
; #pragma unroll
;           for (int i = 0; i < 8; ++i) tile[(ty + 8 * i) * 65 + tx] = v[i];
;           { const int tn = (t + G < 32 * 169) ? t + G : t; const int ktn = tn / 169, ntn = tn - ktn * 169; const int ncl = (ntn * 64 + tx < NIN) ? ntn * 64 + tx : NIN - 1;
; #pragma unroll
;             for (int i = 0; i < 8; ++i) v[i] = src[(size_t)(ktn * 64 + ty + 8 * i) * NIN + ncl]; }
;           LBAR();
; #pragma unroll
;           for (int i = 0; i < 8; ++i) { const int nn = ty + 8 * i; int n = n0 + nn;
;               if (n < NIN) { n = (n < 2560) ? n : (n < 2592 ? n + (C_GLR - 2560) : n - 32); btin[(size_t)n * D + k0 + tx] = f2bf(tile[tx * 65 + nn]); } }
;           LBAR(); } }
;     for (size_t i = (size_t)b * 512 + TID; i < (size_t)(NINP - NIN) * D / 8; i += (size_t)G * 512) *(u32x4*)(btin + (size_t)NIN * D + i * 8) = (u32x4){0u, 0u, 0u, 0u};
;     { const float* src = p.in[25] + (size_t)l * 512 * D; for (int t = (b + 64) % G; t < 8 * 32; t += G) { const int kt = t / 32, ntl = t - kt * 32; conv_tile(TID, src, D, kt * 64, ntl * 64, D, btout, D, 0, false, tile); } }
;     { const float* src = p.in[26] + (size_t)l * 512 * D; for (int t = (b + 128) % G; t < 8 * 32; t += G) { const int kt = t / 32, ntl = t - kt * 32; conv_tile(TID, src, D, kt * 64, ntl * 64, D, btout, D, 512, false, tile); } }
.LBB0_1064:
	s_or_b64 exec, exec, s[28:29]
	s_movk_i32 s2, 0x104
	s_cmpk_gt_i32 s22, 0x151f
	s_waitcnt vmcnt(0)
	v_lshlrev_b32_e32 v10, 8, v12
	v_lshlrev_b32_e32 v182, 1, v12
	v_mul_lo_u32 v8, v13, s2
	v_lshlrev_b32_e32 v11, 2, v13
	v_lshl_add_u32 v9, v12, 2, 0
	s_branch .Lcw_start
.Lcw_start:
	v_lshrrev_b32_e32 v0, 6, v194
	v_and_b32_e32 v1, 63, v194
	v_readlane_b32 s52, v254, 59
	v_readfirstlane_b32 s38, v0
	s_lshl_b32 s39, s22, 3
	s_add_i32 s39, s39, s38
	s_mul_i32 s8, s38, 0x2400
	v_mul_u32_u24_e32 v2, 0x90, v1
	v_add_u32_e32 v2, s8, v2
	v_lshrrev_b32_e32 v5, 3, v1
	v_and_b32_e32 v7, 7, v1
	v_mul_u32_u24_e32 v3, 0x90, v5
	v_lshl_add_u32 v3, v7, 4, v3
	v_add_u32_e32 v3, s8, v3
.Lcw_loop:
	s_cmp_ge_u32 s39, 0x1de0
	s_cbranch_scc1 .Lcw_done
	s_mov_b32 s48, 0x7fffffff
	s_mov_b32 s49, 0
	s_mov_b32 s46, 0x1000
	s_mov_b32 s42, 0x2000
	s_cmp_ge_u32 s39, 0x1520
	s_cbranch_scc1 .Lcw_seg1
	s_mul_i32 s8, s39, 0x183d
	s_lshr_b32 s8, s8, 20
	s_mul_i32 s9, s8, 0xa9
	s_sub_i32 s9, s39, s9
	v_readlane_b32 s40, v254, 8
	v_readlane_b32 s41, v254, 9
	s_mul_i32 s10, s52, 0x5440000
	s_mul_hi_u32 s11, s52, 0x5440000
	s_add_u32 s40, s40, s10
	s_addc_u32 s41, s41, s11
	s_mov_b32 s42, 0xa880
	s_add_u32 s44, s94, 0x49241000
	s_addc_u32 s45, s95, 0
	s_mov_b32 s48, 0x2a20
	s_mov_b32 s49, 1
	s_branch .Lcw_common
.Lcw_seg1:
	s_sub_i32 s23, s39, 0x1520
	s_cmp_ge_u32 s23, 0x400
	s_cbranch_scc1 .Lcw_seg4
	s_lshr_b32 s8, s23, 5
	s_and_b32 s9, s23, 31
	s_add_u32 s44, s94, 0x4bd41000
	s_addc_u32 s45, s95, 0
	s_cmp_ge_u32 s23, 0x100
	s_cbranch_scc1 .Lcw_seg2
	v_readlane_b32 s40, v253, 58
	v_readlane_b32 s41, v253, 59
	s_lshl_b32 s10, s52, 22
	s_branch .Lcw_seg123
.Lcw_seg2:
	s_cmp_ge_u32 s23, 0x200
	s_cbranch_scc1 .Lcw_seg3
	s_sub_i32 s8, s8, 8
	v_readlane_b32 s40, v253, 60
	v_readlane_b32 s41, v253, 61
	s_lshl_b32 s10, s52, 22
	s_add_u32 s44, s44, 0x400
	s_addc_u32 s45, s45, 0
	s_branch .Lcw_seg123
.Lcw_seg3:
	s_sub_i32 s8, s8, 16
	v_readlane_b32 s40, v253, 62
	v_readlane_b32 s41, v253, 63
	s_lshl_b32 s10, s52, 23
	s_add_u32 s44, s44, 0x800
	s_addc_u32 s45, s45, 0
.Lcw_seg123:
	s_add_u32 s40, s40, s10
	s_addc_u32 s41, s41, 0
	s_branch .Lcw_common
.Lcw_seg4:
	s_sub_i32 s23, s23, 0x400
	s_cmp_ge_u32 s23, 0x400
	s_cbranch_scc1 .Lcw_seg5
	s_lshr_b32 s8, s23, 5
	s_and_b32 s9, s23, 31
	v_readlane_b32 s40, v252, 11
	v_readlane_b32 s41, v252, 12
	s_lshl_b32 s10, s52, 24
	s_add_u32 s40, s40, s10
	s_addc_u32 s41, s41, 0
	s_add_u32 s44, s94, 0x4c541000
	s_addc_u32 s45, s95, 0
	s_branch .Lcw_common
.Lcw_seg5:
	s_sub_i32 s23, s23, 0x400
	s_cmp_ge_u32 s23, 0x40
	s_cbranch_scc1 .Lcw_seg6
	s_lshr_b32 s8, s23, 3
	s_and_b32 s9, s23, 7
	v_readlane_b32 s40, v254, 26
	v_readlane_b32 s41, v254, 27
	s_lshl_b32 s10, s52, 20
	s_add_u32 s40, s40, s10
	s_addc_u32 s41, s41, 0
	s_add_u32 s44, s94, 0x4cd41000
	s_addc_u32 s45, s95, 0
	s_mov_b32 s42, 0x800
	s_mov_b32 s46, 0x400
	s_branch .Lcw_common
.Lcw_seg6:
	s_sub_i32 s23, s23, 0x40
	s_lshr_b32 s24, s23, 2
	s_bfe_u32 s8, s23, 0x10001
	s_and_b32 s9, s23, 1
	s_bitcmp1_b32 s24, 3
	s_cbranch_scc1 .Lcw_seg6x
	v_readlane_b32 s40, v254, 40
	v_readlane_b32 s41, v254, 41
	s_branch .Lcw_seg6c
.Lcw_seg6x:
	v_readlane_b32 s40, v254, 44
	v_readlane_b32 s41, v254, 45
.Lcw_seg6c:
	s_lshr_b32 s10, s24, 4
	s_lshl_b32 s11, s52, 1
	s_add_i32 s10, s10, s11
	s_lshl_b32 s10, s10, 3
	s_and_b32 s11, s24, 7
	s_add_i32 s10, s10, s11
	s_lshl_b32 s10, s10, 16
	s_add_u32 s40, s40, s10
	s_addc_u32 s41, s41, 0
	s_add_u32 s44, s94, 0x4cdc1000
	s_addc_u32 s45, s95, 0
	s_lshl_b32 s10, s24, 15
	s_add_u32 s44, s44, s10
	s_addc_u32 s45, s45, 0
	s_mov_b32 s42, 0x200
	s_mov_b32 s46, 0x100
.Lcw_common:
	s_mul_i32 s10, s8, s42
	s_lshl_b32 s10, s10, 6
	s_add_u32 s40, s40, s10
	s_addc_u32 s41, s41, 0
	s_lshl_b32 s10, s9, 8
	s_add_u32 s40, s40, s10
	s_addc_u32 s41, s41, 0
	s_lshl_b32 s10, s8, 7
	s_add_u32 s44, s44, s10
	s_addc_u32 s45, s45, 0
	s_lshl_b32 s47, s9, 6
	s_sub_i32 s10, s48, s47
	s_add_i32 s10, s10, -1
	s_min_u32 s10, s10, 63
	v_min_u32_e32 v4, s10, v1
	v_lshlrev_b32_e32 v4, 2, v4
	v_mul_lo_u32 v6, v5, s46
	v_lshl_add_u32 v6, v7, 4, v6
	global_load_dword v64, v4, s[40:41]
	s_add_u32 s40, s40, s42
	s_addc_u32 s41, s41, 0
	global_load_dword v65, v4, s[40:41]
	s_add_u32 s40, s40, s42
	s_addc_u32 s41, s41, 0
	global_load_dword v66, v4, s[40:41]
	s_add_u32 s40, s40, s42
	s_addc_u32 s41, s41, 0
	global_load_dword v67, v4, s[40:41]
	s_add_u32 s40, s40, s42
	s_addc_u32 s41, s41, 0
	global_load_dword v68, v4, s[40:41]
	s_add_u32 s40, s40, s42
	s_addc_u32 s41, s41, 0
	global_load_dword v69, v4, s[40:41]
	s_add_u32 s40, s40, s42
	s_addc_u32 s41, s41, 0
	global_load_dword v70, v4, s[40:41]
	s_add_u32 s40, s40, s42
	s_addc_u32 s41, s41, 0
	global_load_dword v71, v4, s[40:41]
	s_add_u32 s40, s40, s42
	s_addc_u32 s41, s41, 0
	global_load_dword v72, v4, s[40:41]
	s_add_u32 s40, s40, s42
	s_addc_u32 s41, s41, 0
	global_load_dword v73, v4, s[40:41]
	s_add_u32 s40, s40, s42
	s_addc_u32 s41, s41, 0
	global_load_dword v74, v4, s[40:41]
	s_add_u32 s40, s40, s42
	s_addc_u32 s41, s41, 0
	global_load_dword v75, v4, s[40:41]
	s_add_u32 s40, s40, s42
	s_addc_u32 s41, s41, 0
	global_load_dword v76, v4, s[40:41]
	s_add_u32 s40, s40, s42
	s_addc_u32 s41, s41, 0
	global_load_dword v77, v4, s[40:41]
	s_add_u32 s40, s40, s42
	s_addc_u32 s41, s41, 0
	global_load_dword v78, v4, s[40:41]
	s_add_u32 s40, s40, s42
	s_addc_u32 s41, s41, 0
	global_load_dword v79, v4, s[40:41]
	s_add_u32 s40, s40, s42
	s_addc_u32 s41, s41, 0
	global_load_dword v80, v4, s[40:41]
	s_add_u32 s40, s40, s42
	s_addc_u32 s41, s41, 0
	global_load_dword v81, v4, s[40:41]
	s_add_u32 s40, s40, s42
	s_addc_u32 s41, s41, 0
	global_load_dword v82, v4, s[40:41]
; #define LAS __attribute__((address_space(3)))
; #define LBAR() do { asm volatile("s_waitcnt lgkmcnt(0)" ::: "memory"); __builtin_amdgcn_s_barrier(); asm volatile("" ::: "memory"); } while (0)
; __device__ __forceinline__ bf16_t f2bf(float f) { return (bf16_t)(cvt_pk_bf16(f, 0.f) & 0xffffu); }
; __device__ __forceinline__ void conv_tile(const int TID, const float* src, int ldn, int k0, int n0, int nvalid, bf16_t* dst, int ldd, int kofs, bool mapin, LAS float* tile) {
;     const int tx = TID & 63, ty = TID >> 6;
;     const int ncl = (n0 + tx < nvalid) ? n0 + tx : nvalid - 1;
; #pragma unroll
;     for (int i = 0; i < 8; ++i) { const int k = ty + 8 * i; tile[k * 65 + tx] = src[(size_t)(k0 + k) * ldn + ncl]; }
;     __syncthreads();
; #pragma unroll
;     for (int i = 0; i < 8; ++i) { const int nn = ty + 8 * i; int n = n0 + nn;
;         if (n < nvalid) { if (mapin) n = (n < 2560) ? n : (n < 2592 ? n + (C_GLR - 2560) : n - 32); dst[(size_t)n * ldd + kofs + k0 + tx] = f2bf(tile[tx * 65 + nn]); } }
; __device__ __forceinline__ void convert_weights(const int TID, const int BID, const Params& p, int l, LAS float* tile) {
;     ...
;     { const float* src = p.in[4] + (size_t)l * D * NIN; const int tx = TID & 63, ty = TID >> 6; float v[8];
;       { const int t = b < 32 * 169 ? b : 0; const int kt = t / 169, ntl = t - kt * 169; const int ncl = (ntl * 64 + tx < NIN) ? ntl * 64 + tx : NIN - 1;
; #pragma unroll
;         for (int i = 0; i < 8; ++i) v[i] = src[(size_t)(kt * 64 + ty + 8 * i) * NIN + ncl]; }
;       for (int t = b; t < 32 * 169; t += G) { const int kt = t / 169, ntl = t - kt * 169, k0 = kt * 64, n0 = ntl * 64;
; #pragma unroll
;           for (int i = 0; i < 8; ++i) tile[(ty + 8 * i) * 65 + tx] = v[i];
;           { const int tn = (t + G < 32 * 169) ? t + G : t; const int ktn = tn / 169, ntn = tn - ktn * 169; const int ncl = (ntn * 64 + tx < NIN) ? ntn * 64 + tx : NIN - 1;
; #pragma unroll
;             for (int i = 0; i < 8; ++i) v[i] = src[(size_t)(ktn * 64 + ty + 8 * i) * NIN + ncl]; }
;           LBAR();
; #pragma unroll
;           for (int i = 0; i < 8; ++i) { const int nn = ty + 8 * i; int n = n0 + nn;
;               if (n < NIN) { n = (n < 2560) ? n : (n < 2592 ? n + (C_GLR - 2560) : n - 32); btin[(size_t)n * D + k0 + tx] = f2bf(tile[tx * 65 + nn]); } }
;           LBAR(); } }
	s_add_u32 s40, s40, s42
	s_addc_u32 s41, s41, 0
	global_load_dword v83, v4, s[40:41]
	s_add_u32 s40, s40, s42
	s_addc_u32 s41, s41, 0
	global_load_dword v84, v4, s[40:41]
	s_add_u32 s40, s40, s42
	s_addc_u32 s41, s41, 0
	global_load_dword v85, v4, s[40:41]
	s_add_u32 s40, s40, s42
	s_addc_u32 s41, s41, 0
	global_load_dword v86, v4, s[40:41]
	s_add_u32 s40, s40, s42
	s_addc_u32 s41, s41, 0
	global_load_dword v87, v4, s[40:41]
	s_add_u32 s40, s40, s42
	s_addc_u32 s41, s41, 0
	global_load_dword v88, v4, s[40:41]
	s_add_u32 s40, s40, s42
	s_addc_u32 s41, s41, 0
	global_load_dword v89, v4, s[40:41]
	s_add_u32 s40, s40, s42
	s_addc_u32 s41, s41, 0
	global_load_dword v90, v4, s[40:41]
	s_add_u32 s40, s40, s42
	s_addc_u32 s41, s41, 0
	global_load_dword v91, v4, s[40:41]
	s_add_u32 s40, s40, s42
	s_addc_u32 s41, s41, 0
	global_load_dword v92, v4, s[40:41]
	s_add_u32 s40, s40, s42
	s_addc_u32 s41, s41, 0
	global_load_dword v93, v4, s[40:41]
	s_add_u32 s40, s40, s42
	s_addc_u32 s41, s41, 0
	global_load_dword v94, v4, s[40:41]
	s_add_u32 s40, s40, s42
	s_addc_u32 s41, s41, 0
	global_load_dword v95, v4, s[40:41]
	s_add_u32 s40, s40, s42
	s_addc_u32 s41, s41, 0
	global_load_dword v96, v4, s[40:41]
	s_add_u32 s40, s40, s42
	s_addc_u32 s41, s41, 0
	global_load_dword v97, v4, s[40:41]
	s_add_u32 s40, s40, s42
	s_addc_u32 s41, s41, 0
	global_load_dword v98, v4, s[40:41]
	s_add_u32 s40, s40, s42
	s_addc_u32 s41, s41, 0
	global_load_dword v99, v4, s[40:41]
	s_add_u32 s40, s40, s42
	s_addc_u32 s41, s41, 0
	global_load_dword v100, v4, s[40:41]
	s_add_u32 s40, s40, s42
	s_addc_u32 s41, s41, 0
	global_load_dword v101, v4, s[40:41]
	s_add_u32 s40, s40, s42
	s_addc_u32 s41, s41, 0
	global_load_dword v102, v4, s[40:41]
	s_add_u32 s40, s40, s42
	s_addc_u32 s41, s41, 0
	global_load_dword v103, v4, s[40:41]
	s_add_u32 s40, s40, s42
	s_addc_u32 s41, s41, 0
	global_load_dword v104, v4, s[40:41]
	s_add_u32 s40, s40, s42
	s_addc_u32 s41, s41, 0
	global_load_dword v105, v4, s[40:41]
	s_add_u32 s40, s40, s42
	s_addc_u32 s41, s41, 0
	global_load_dword v106, v4, s[40:41]
	s_add_u32 s40, s40, s42
	s_addc_u32 s41, s41, 0
	global_load_dword v107, v4, s[40:41]
	s_add_u32 s40, s40, s42
	s_addc_u32 s41, s41, 0
	global_load_dword v108, v4, s[40:41]
	s_add_u32 s40, s40, s42
	s_addc_u32 s41, s41, 0
	global_load_dword v109, v4, s[40:41]
	s_add_u32 s40, s40, s42
	s_addc_u32 s41, s41, 0
	global_load_dword v110, v4, s[40:41]
	s_add_u32 s40, s40, s42
	s_addc_u32 s41, s41, 0
	global_load_dword v111, v4, s[40:41]
	s_add_u32 s40, s40, s42
	s_addc_u32 s41, s41, 0
	global_load_dword v112, v4, s[40:41]
	s_add_u32 s40, s40, s42
	s_addc_u32 s41, s41, 0
	global_load_dword v113, v4, s[40:41]
	s_add_u32 s40, s40, s42
	s_addc_u32 s41, s41, 0
	global_load_dword v114, v4, s[40:41]
	s_add_u32 s40, s40, s42
	s_addc_u32 s41, s41, 0
	global_load_dword v115, v4, s[40:41]
	s_add_u32 s40, s40, s42
	s_addc_u32 s41, s41, 0
	global_load_dword v116, v4, s[40:41]
	s_add_u32 s40, s40, s42
	s_addc_u32 s41, s41, 0
	global_load_dword v117, v4, s[40:41]
	s_add_u32 s40, s40, s42
	s_addc_u32 s41, s41, 0
	global_load_dword v118, v4, s[40:41]
	s_add_u32 s40, s40, s42
	s_addc_u32 s41, s41, 0
	global_load_dword v119, v4, s[40:41]
	s_add_u32 s40, s40, s42
	s_addc_u32 s41, s41, 0
	global_load_dword v120, v4, s[40:41]
	s_add_u32 s40, s40, s42
	s_addc_u32 s41, s41, 0
	global_load_dword v121, v4, s[40:41]
	s_add_u32 s40, s40, s42
	s_addc_u32 s41, s41, 0
	global_load_dword v122, v4, s[40:41]
	s_add_u32 s40, s40, s42
	s_addc_u32 s41, s41, 0
	global_load_dword v123, v4, s[40:41]
	s_add_u32 s40, s40, s42
	s_addc_u32 s41, s41, 0
	global_load_dword v124, v4, s[40:41]
	s_add_u32 s40, s40, s42
	s_addc_u32 s41, s41, 0
	global_load_dword v125, v4, s[40:41]
	s_add_u32 s40, s40, s42
	s_addc_u32 s41, s41, 0
	global_load_dword v126, v4, s[40:41]
	s_add_u32 s40, s40, s42
	s_addc_u32 s41, s41, 0
	global_load_dword v127, v4, s[40:41]
	s_waitcnt vmcnt(0)
	v_cvt_pk_bf16_f32 v32, v64, v65
	v_cvt_pk_bf16_f32 v33, v66, v67
	v_cvt_pk_bf16_f32 v34, v68, v69
	v_cvt_pk_bf16_f32 v35, v70, v71
	v_cvt_pk_bf16_f32 v36, v72, v73
	v_cvt_pk_bf16_f32 v37, v74, v75
	v_cvt_pk_bf16_f32 v38, v76, v77
	v_cvt_pk_bf16_f32 v39, v78, v79
	v_cvt_pk_bf16_f32 v40, v80, v81
	v_cvt_pk_bf16_f32 v41, v82, v83
	v_cvt_pk_bf16_f32 v42, v84, v85
	v_cvt_pk_bf16_f32 v43, v86, v87
	v_cvt_pk_bf16_f32 v44, v88, v89
	v_cvt_pk_bf16_f32 v45, v90, v91
	v_cvt_pk_bf16_f32 v46, v92, v93
	v_cvt_pk_bf16_f32 v47, v94, v95
	v_cvt_pk_bf16_f32 v48, v96, v97
	v_cvt_pk_bf16_f32 v49, v98, v99
	v_cvt_pk_bf16_f32 v50, v100, v101
	v_cvt_pk_bf16_f32 v51, v102, v103
	v_cvt_pk_bf16_f32 v52, v104, v105
	v_cvt_pk_bf16_f32 v53, v106, v107
	v_cvt_pk_bf16_f32 v54, v108, v109
	v_cvt_pk_bf16_f32 v55, v110, v111
	v_cvt_pk_bf16_f32 v56, v112, v113
	v_cvt_pk_bf16_f32 v57, v114, v115
	v_cvt_pk_bf16_f32 v58, v116, v117
	v_cvt_pk_bf16_f32 v59, v118, v119
	v_cvt_pk_bf16_f32 v60, v120, v121
	v_cvt_pk_bf16_f32 v61, v122, v123
	v_cvt_pk_bf16_f32 v62, v124, v125
	v_cvt_pk_bf16_f32 v63, v126, v127
	ds_write_b128 v2, v[32:35] offset:0
	ds_write_b128 v2, v[36:39] offset:16
	ds_write_b128 v2, v[40:43] offset:32
	ds_write_b128 v2, v[44:47] offset:48
	ds_write_b128 v2, v[48:51] offset:64
	ds_write_b128 v2, v[52:55] offset:80
	ds_write_b128 v2, v[56:59] offset:96
	ds_write_b128 v2, v[60:63] offset:112
	s_waitcnt lgkmcnt(0)
	ds_read_b128 v[128:131], v3 offset:0
	ds_read_b128 v[132:135], v3 offset:1152
	ds_read_b128 v[136:139], v3 offset:2304
	ds_read_b128 v[140:143], v3 offset:3456
	ds_read_b128 v[144:147], v3 offset:4608
	ds_read_b128 v[148:151], v3 offset:5760
	ds_read_b128 v[152:155], v3 offset:6912
	ds_read_b128 v[156:159], v3 offset:8064
	s_waitcnt lgkmcnt(0)
	s_add_i32 s10, s47, 0
	s_cmp_ge_u32 s10, s48
	s_cbranch_scc1 .Lcw_skip0
	s_sub_i32 s11, s10, 32
	s_cmp_lt_u32 s10, 0xa00
	s_cselect_b32 s11, s10, s11
	s_add_i32 s28, s10, 0x2000
	s_sub_i32 s29, s10, 0xa00
	s_cmp_lt_u32 s29, 32
	s_cselect_b32 s11, s28, s11
	s_cmp_lg_u32 s49, 0
	s_cselect_b32 s11, s11, s10
	s_mul_i32 s11, s11, s46
	s_add_u32 s50, s44, s11
	s_addc_u32 s51, s45, 0
	global_store_dwordx4 v6, v[128:131], s[50:51]
; #define LBAR() do { asm volatile("s_waitcnt lgkmcnt(0)" ::: "memory"); __builtin_amdgcn_s_barrier(); asm volatile("" ::: "memory"); } while (0)
; __device__ __forceinline__ bf16_t f2bf(float f) { return (bf16_t)(cvt_pk_bf16(f, 0.f) & 0xffffu); }
; __device__ __forceinline__ void convert_weights(const int TID, const int BID, const Params& p, int l, LAS float* tile) {
;     ...
;           LBAR();
; #pragma unroll
;           for (int i = 0; i < 8; ++i) { const int nn = ty + 8 * i; int n = n0 + nn;
;               if (n < NIN) { n = (n < 2560) ? n : (n < 2592 ? n + (C_GLR - 2560) : n - 32); btin[(size_t)n * D + k0 + tx] = f2bf(tile[tx * 65 + nn]); } }
;           LBAR(); } }
;     for (size_t i = (size_t)b * 512 + TID; i < (size_t)(NINP - NIN) * D / 8; i += (size_t)G * 512) *(u32x4*)(btin + (size_t)NIN * D + i * 8) = (u32x4){0u, 0u, 0u, 0u};
;     { const float* src = p.in[25] + (size_t)l * 512 * D; for (int t = (b + 64) % G; t < 8 * 32; t += G) { const int kt = t / 32, ntl = t - kt * 32; conv_tile(TID, src, D, kt * 64, ntl * 64, D, btout, D, 0, false, tile); } }
;     { const float* src = p.in[26] + (size_t)l * 512 * D; for (int t = (b + 128) % G; t < 8 * 32; t += G) { const int kt = t / 32, ntl = t - kt * 32; conv_tile(TID, src, D, kt * 64, ntl * 64, D, btout, D, 512, false, tile); } }
;     { const float* src = p.in[27] + (size_t)l * 1024 * D; for (int t = b; t < 16 * 32; t += G) { const int kt = t / 32, ntl = t - kt * 32; conv_tile(TID, src, D, kt * 64, ntl * 64, D, btout, D, 1024, false, tile); } }
;     { const float* src = p.in[28] + (size_t)l * D * D; for (int t = b; t < 32 * 32; t += G) { const int kt = t / 32, ntl = t - kt * 32; conv_tile(TID, src, D, kt * 64, ntl * 64, D, bto, D, 0, false, tile); } }
;     { const float* src = p.in[13] + (size_t)l * 512 * 512; for (int t = (b + 192) % G; t < 8 * 8; t += G) { const int kt = t / 8, ntl = t - kt * 8; conv_tile(TID, src, 512, kt * 64, ntl * 64, 512, btglu, 512, 0, false, tile); } }
;     for (int t = (b + 32) % G; t < 128; t += G) { const int mat = t >> 2, sub = t & 3;
;         const int dk = mat >> 3, nb = mat & 7, d = dk >> 1, kind = dk & 1;
;         const float* src = p.in[kind ? 22 : 20] + ((size_t)(l * 2 + d) * 8 + nb) * 128 * 128;
;         conv_tile(TID, src, 128, (sub >> 1) * 64, (sub & 1) * 64, 128, btlru + (size_t)mat * 128 * 128, 128, 0, false, tile); }
.Lcw_skip0:
	s_add_i32 s10, s47, 8
	s_cmp_ge_u32 s10, s48
	s_cbranch_scc1 .Lcw_skip1
	s_sub_i32 s11, s10, 32
	s_cmp_lt_u32 s10, 0xa00
	s_cselect_b32 s11, s10, s11
	s_add_i32 s28, s10, 0x2000
	s_sub_i32 s29, s10, 0xa00
	s_cmp_lt_u32 s29, 32
	s_cselect_b32 s11, s28, s11
	s_cmp_lg_u32 s49, 0
	s_cselect_b32 s11, s11, s10
	s_mul_i32 s11, s11, s46
	s_add_u32 s50, s44, s11
	s_addc_u32 s51, s45, 0
	global_store_dwordx4 v6, v[132:135], s[50:51]
.Lcw_skip1:
	s_add_i32 s10, s47, 16
	s_cmp_ge_u32 s10, s48
	s_cbranch_scc1 .Lcw_skip2
	s_sub_i32 s11, s10, 32
	s_cmp_lt_u32 s10, 0xa00
	s_cselect_b32 s11, s10, s11
	s_add_i32 s28, s10, 0x2000
	s_sub_i32 s29, s10, 0xa00
	s_cmp_lt_u32 s29, 32
	s_cselect_b32 s11, s28, s11
	s_cmp_lg_u32 s49, 0
	s_cselect_b32 s11, s11, s10
	s_mul_i32 s11, s11, s46
	s_add_u32 s50, s44, s11
	s_addc_u32 s51, s45, 0
	global_store_dwordx4 v6, v[136:139], s[50:51]
.Lcw_skip2:
	s_add_i32 s10, s47, 24
	s_cmp_ge_u32 s10, s48
	s_cbranch_scc1 .Lcw_skip3
	s_sub_i32 s11, s10, 32
	s_cmp_lt_u32 s10, 0xa00
	s_cselect_b32 s11, s10, s11
	s_add_i32 s28, s10, 0x2000
	s_sub_i32 s29, s10, 0xa00
	s_cmp_lt_u32 s29, 32
	s_cselect_b32 s11, s28, s11
	s_cmp_lg_u32 s49, 0
	s_cselect_b32 s11, s11, s10
	s_mul_i32 s11, s11, s46
	s_add_u32 s50, s44, s11
	s_addc_u32 s51, s45, 0
	global_store_dwordx4 v6, v[140:143], s[50:51]
.Lcw_skip3:
	s_add_i32 s10, s47, 32
	s_cmp_ge_u32 s10, s48
	s_cbranch_scc1 .Lcw_skip4
	s_sub_i32 s11, s10, 32
	s_cmp_lt_u32 s10, 0xa00
	s_cselect_b32 s11, s10, s11
	s_add_i32 s28, s10, 0x2000
	s_sub_i32 s29, s10, 0xa00
	s_cmp_lt_u32 s29, 32
	s_cselect_b32 s11, s28, s11
	s_cmp_lg_u32 s49, 0
	s_cselect_b32 s11, s11, s10
	s_mul_i32 s11, s11, s46
	s_add_u32 s50, s44, s11
	s_addc_u32 s51, s45, 0
	global_store_dwordx4 v6, v[144:147], s[50:51]
.Lcw_skip4:
	s_add_i32 s10, s47, 40
	s_cmp_ge_u32 s10, s48
	s_cbranch_scc1 .Lcw_skip5
	s_sub_i32 s11, s10, 32
	s_cmp_lt_u32 s10, 0xa00
	s_cselect_b32 s11, s10, s11
	s_add_i32 s28, s10, 0x2000
	s_sub_i32 s29, s10, 0xa00
	s_cmp_lt_u32 s29, 32
	s_cselect_b32 s11, s28, s11
	s_cmp_lg_u32 s49, 0
	s_cselect_b32 s11, s11, s10
	s_mul_i32 s11, s11, s46
	s_add_u32 s50, s44, s11
	s_addc_u32 s51, s45, 0
	global_store_dwordx4 v6, v[148:151], s[50:51]
.Lcw_skip5:
	s_add_i32 s10, s47, 48
	s_cmp_ge_u32 s10, s48
	s_cbranch_scc1 .Lcw_skip6
	s_sub_i32 s11, s10, 32
	s_cmp_lt_u32 s10, 0xa00
	s_cselect_b32 s11, s10, s11
	s_add_i32 s28, s10, 0x2000
	s_sub_i32 s29, s10, 0xa00
	s_cmp_lt_u32 s29, 32
	s_cselect_b32 s11, s28, s11
	s_cmp_lg_u32 s49, 0
	s_cselect_b32 s11, s11, s10
	s_mul_i32 s11, s11, s46
	s_add_u32 s50, s44, s11
	s_addc_u32 s51, s45, 0
	global_store_dwordx4 v6, v[152:155], s[50:51]
.Lcw_skip6:
	s_add_i32 s10, s47, 56
	s_cmp_ge_u32 s10, s48
	s_cbranch_scc1 .Lcw_skip7
	s_sub_i32 s11, s10, 32
	s_cmp_lt_u32 s10, 0xa00
	s_cselect_b32 s11, s10, s11
	s_add_i32 s28, s10, 0x2000
	s_sub_i32 s29, s10, 0xa00
	s_cmp_lt_u32 s29, 32
	s_cselect_b32 s11, s28, s11
	s_cmp_lg_u32 s49, 0
	s_cselect_b32 s11, s11, s10
	s_mul_i32 s11, s11, s46
	s_add_u32 s50, s44, s11
	s_addc_u32 s51, s45, 0
	global_store_dwordx4 v6, v[156:159], s[50:51]
.Lcw_skip7:
	s_add_i32 s39, s39, 0x800
	s_branch .Lcw_loop
.Lcw_done:
.LBB0_1083:
	s_ashr_i32 s23, s22, 31
	s_lshl_b64 s[2:3], s[22:23], 9
	v_ashrrev_i32_e32 v195, 31, v194
	v_lshl_add_u64 v[0:1], s[2:3], 0, v[194:195]
	s_mov_b64 s[2:3], 0xe000
	v_cmp_gt_u64_e32 vcc, s[2:3], v[0:1]
	s_and_saveexec_b64 s[2:3], vcc
	v_readlane_b32 s8, v254, 48
	v_readlane_b32 s10, v253, 54
	v_readlane_b32 s9, v254, 49
	v_readlane_b32 s11, v253, 55
	s_cbranch_execz .LBB0_1086
	s_lshl_b64 s[28:29], s[22:23], 13
	s_add_u32 s28, s94, s28
	s_addc_u32 s29, s95, s29
	v_lshl_add_u64 v[2:3], v[194:195], 4, s[28:29]
	s_mov_b64 s[28:29], 0x4bc61000
	v_lshl_add_u64 v[2:3], v[2:3], 0, s[28:29]
	s_mov_b64 s[28:29], 0

; __device__ __forceinline__ void convert_weights(const int TID, const int BID, const Params& p, int l, LAS float* tile) {
;     ...
;     for (size_t i = (size_t)b * 512 + TID; i < (size_t)(NINP - NIN) * D / 8; i += (size_t)G * 512) *(u32x4*)(btin + (size_t)NIN * D + i * 8) = (u32x4){0u, 0u, 0u, 0u};
;     { const float* src = p.in[25] + (size_t)l * 512 * D; for (int t = (b + 64) % G; t < 8 * 32; t += G) { const int kt = t / 32, ntl = t - kt * 32; conv_tile(TID, src, D, kt * 64, ntl * 64, D, btout, D, 0, false, tile); } }
;     { const float* src = p.in[26] + (size_t)l * 512 * D; for (int t = (b + 128) % G; t < 8 * 32; t += G) { const int kt = t / 32, ntl = t - kt * 32; conv_tile(TID, src, D, kt * 64, ntl * 64, D, btout, D, 512, false, tile); } }
;     { const float* src = p.in[27] + (size_t)l * 1024 * D; for (int t = b; t < 16 * 32; t += G) { const int kt = t / 32, ntl = t - kt * 32; conv_tile(TID, src, D, kt * 64, ntl * 64, D, btout, D, 1024, false, tile); } }
;     { const float* src = p.in[28] + (size_t)l * D * D; for (int t = b; t < 32 * 32; t += G) { const int kt = t / 32, ntl = t - kt * 32; conv_tile(TID, src, D, kt * 64, ntl * 64, D, bto, D, 0, false, tile); } }
;     { const float* src = p.in[13] + (size_t)l * 512 * 512; for (int t = (b + 192) % G; t < 8 * 8; t += G) { const int kt = t / 8, ntl = t - kt * 8; conv_tile(TID, src, 512, kt * 64, ntl * 64, 512, btglu, 512, 0, false, tile); } }
;     for (int t = (b + 32) % G; t < 128; t += G) { const int mat = t >> 2, sub = t & 3;
;         const int dk = mat >> 3, nb = mat & 7, d = dk >> 1, kind = dk & 1;
;         const float* src = p.in[kind ? 22 : 20] + ((size_t)(l * 2 + d) * 8 + nb) * 128 * 128;
;         conv_tile(TID, src, 128, (sub >> 1) * 64, (sub & 1) * 64, 128, btlru + (size_t)mat * 128 * 128, 128, 0, false, tile); }
; }
.LBB0_1086:
	s_or_b64 exec, exec, s[2:3]
	s_branch .LBB0_1200
